# GEMM phase prologues: second LDS-DMA batch (stage 1 K-tiles) issued together with the first instead of after the first wait+barrier
# baseline (speedup 1.0000x reference)
.LBB0_115:
	s_and_b64 vcc, exec, s[4:5]
	s_cbranch_vccnz .LBB0_177
	v_ashrrev_i32_e32 v1, 31, v8
	v_lshrrev_b32_e32 v1, 26, v1
	v_add_u32_e32 v1, v8, v1
	v_ashrrev_i32_e32 v9, 6, v1
	v_bfe_i32 v1, v8, 27, 1
	v_lshlrev_b32_e32 v0, 4, v8
	v_lshrrev_b32_e32 v1, 22, v1
	v_add_u32_e32 v1, v0, v1
	v_and_b32_e32 v1, 0xfffffc00, v1
	v_sub_u32_e32 v1, v0, v1
	v_lshrrev_b32_e32 v2, 4, v1
	v_bitop3_b32 v1, v2, v1, 32 bitop3:0x6c
	v_ashrrev_i32_e32 v3, 31, v1
	v_lshrrev_b32_e32 v3, 26, v3
	v_add_u32_e32 v3, v1, v3
	v_lshlrev_b32_e32 v2, 3, v9
	s_waitcnt lgkmcnt(0)
	v_ashrrev_i32_e32 v10, 6, v3
	v_and_b32_e32 v3, 0xc0, v3
	v_and_b32_e32 v2, -16, v2
	v_sub_u32_e32 v1, v1, v3
	v_add_u32_e32 v2, v10, v2
	v_ashrrev_i16_sdwa v1, v252, sext(v1) dst_sel:DWORD dst_unused:UNUSED_PAD src0_sel:DWORD src1_sel:BYTE_0
	v_lshlrev_b32_e32 v4, 5, v9
	v_bfe_i32 v11, v1, 0, 16
	v_lshlrev_b32_e32 v1, 1, v2
	v_lshrrev_b32_e32 v3, 2, v2
	v_and_b32_e32 v5, 3, v10
	s_mov_b32 s5, 0x1fffe0
	v_and_b32_e32 v4, 32, v4
	v_and_b32_e32 v1, 24, v1
	v_and_b32_e32 v3, 4, v3
	v_and_or_b32 v5, v2, s5, v5
	v_or3_b32 v1, v5, v3, v1
	v_add_lshl_u32 v3, v4, v11, 1
	v_add_u32_e32 v0, 0x2000, v0
	v_lshl_add_u32 v192, v1, 11, v3
	v_ashrrev_i32_e32 v1, 31, v0
	v_lshrrev_b32_e32 v1, 22, v1
	v_add_u32_e32 v1, v0, v1
	v_ashrrev_i32_e32 v12, 10, v1
	v_mul_i32_i24_e32 v1, 0x400, v12
	v_sub_u32_e32 v0, v0, v1
	v_lshrrev_b32_e32 v1, 4, v0
	v_bitop3_b32 v0, v1, v0, 32 bitop3:0x6c
	v_lshl_add_u32 v196, v2, 11, v3
	v_ashrrev_i32_e32 v2, 31, v0
	v_lshrrev_b32_e32 v2, 26, v2
	v_lshlrev_b32_e32 v1, 3, v12
	v_add_u32_e32 v2, v0, v2
	v_and_b32_e32 v1, -16, v1
	v_ashrrev_i32_e32 v13, 6, v2
	s_ashr_i32 s4, s6, 6
	v_add_u32_e32 v1, v13, v1
	v_and_b32_e32 v2, 0xc0, v2
	v_and_b32_e32 v4, 3, v13
	s_ashr_i32 s31, s30, 31
	s_ashr_i32 s29, s28, 31
	v_sub_u32_e32 v0, v0, v2
	v_and_or_b32 v4, v1, s5, v4
	s_ashr_i32 s5, s6, 8
	s_lshl_b32 s38, s4, 10
	s_lshl_b64 s[14:15], s[30:31], 19
	s_lshl_b64 s[8:9], s[28:29], 19
	v_ashrrev_i16_sdwa v0, v252, sext(v0) dst_sel:DWORD dst_unused:UNUSED_PAD src0_sel:DWORD src1_sel:BYTE_0
	s_add_u32 s8, s10, s8
	v_lshlrev_b32_e32 v3, 5, v12
	v_bfe_i32 v14, v0, 0, 16
	v_lshlrev_b32_e32 v0, 1, v1
	v_lshrrev_b32_e32 v2, 2, v1
	s_addc_u32 s9, s11, s9
	s_add_i32 s39, s38, 0
	v_and_b32_e32 v3, 32, v3
	v_and_b32_e32 v0, 24, v0
	v_and_b32_e32 v2, 4, v2
	s_add_i32 m0, s39, 0x10000
	v_or3_b32 v0, v4, v2, v0
	v_add_lshl_u32 v2, v3, v14, 1
	global_load_lds_dwordx4 v192, s[8:9]
	s_add_i32 m0, s39, 0x12000
	v_lshl_add_u32 v200, v0, 11, v2
	s_add_u32 s16, s8, 0x40000
	global_load_lds_dwordx4 v200, s[8:9]
	s_addc_u32 s17, s9, 0
	s_add_i32 m0, s39, 0x14000
	v_lshl_add_u32 v198, v1, 11, v2
	global_load_lds_dwordx4 v192, s[16:17]
	s_add_i32 m0, s39, 0x16000
	s_add_u32 s34, s12, s14
	s_addc_u32 s35, s13, s15
	s_add_i32 s40, s39, 0x2000
	global_load_lds_dwordx4 v200, s[16:17]
	s_mov_b32 m0, s39
	s_add_u32 s14, s34, 0x40000
	global_load_lds_dwordx4 v196, s[34:35]
	s_mov_b32 m0, s40
	s_addc_u32 s15, s35, 0
	s_add_i32 s41, s39, 0x4000
	global_load_lds_dwordx4 v198, s[34:35]
	s_mov_b32 m0, s41
	s_add_i32 s42, s39, 0x6000
	global_load_lds_dwordx4 v196, s[14:15]
	s_mov_b32 m0, s42
	v_mov_b32_e32 v201, v193
	global_load_lds_dwordx4 v198, s[14:15]
	v_mov_b32_e32 v197, v193
	v_mov_b32_e32 v199, v193
	v_lshl_add_u64 v[6:7], s[8:9], 0, v[192:193]
	v_lshl_add_u64 v[4:5], s[8:9], 0, v[200:201]
	v_lshl_add_u64 v[0:1], s[34:35], 0, v[196:197]
	v_lshl_add_u64 v[2:3], s[34:35], 0, v[198:199]
	s_add_i32 m0, s39, 0x18000
	v_lshl_add_u64 v[6:7], v[6:7], 0, s[2:3]
	s_nop 0
	global_load_lds_dwordx4 v[6:7], off
	v_lshl_add_u64 v[4:5], v[4:5], 0, s[2:3]
	s_add_i32 m0, s39, 0x1a000
	s_add_i32 s43, s39, 0x8000
	s_add_i32 s44, s39, 0xa000
	global_load_lds_dwordx4 v[4:5], off
	v_lshl_add_u64 v[0:1], v[0:1], 0, s[2:3]
	s_mov_b32 m0, s43
	s_add_u32 s16, s8, 0x40080
	global_load_lds_dwordx4 v[0:1], off
	v_lshl_add_u64 v[0:1], v[2:3], 0, s[2:3]
	s_mov_b32 m0, s44
	s_addc_u32 s17, s9, 0
	global_load_lds_dwordx4 v[0:1], off
	s_add_i32 m0, s39, 0x1c000
	v_lshl_add_u64 v[0:1], s[16:17], 0, v[192:193]
	global_load_lds_dwordx4 v[0:1], off
	v_lshl_add_u64 v[0:1], s[16:17], 0, v[200:201]
	s_add_i32 m0, s39, 0x1e000
	s_nop 0
	global_load_lds_dwordx4 v[0:1], off
	s_cmp_eq_u32 s5, 1
	s_cselect_b64 s[14:15], -1, 0
	s_cmp_lg_u32 s5, 1
	s_cbranch_scc1 .LBB0_118
	s_barrier
.LBB0_118:
	s_and_b32 s4, s4, 3
	s_lshl_b32 s7, s5, 13
	s_lshl_b32 s18, s4, 12
	s_waitcnt vmcnt(8)
	s_barrier
	s_cmpk_lt_u32 s6, 0x100
	v_bfe_u32 v1, v8, 4, 2
	v_and_b32_e32 v0, 15, v8
	v_lshlrev_b32_e32 v3, 4, v1
	v_lshl_or_b32 v232, s5, 6, v0
	v_lshl_or_b32 v0, v0, 6, v3
	v_lshlrev_b32_e32 v3, 2, v8
	v_and_b32_e32 v3, 32, v3
	v_lshlrev_b32_e32 v2, 3, v1
	v_bitop3_b32 v4, v0, s7, v3 bitop3:0xde
	s_cselect_b64 s[16:17], -1, 0
	s_bitcmp0_b32 s6, 6
	v_readlane_b32 s6, v253, 11
	v_bitop3_b32 v233, v0, s18, v3 bitop3:0xde
	v_lshl_or_b32 v234, s4, 5, v2
	v_cmp_gt_u32_e64 s[4:5], 2, v1
	v_and_b32_e32 v0, 16, v8
	v_mov_b32_e32 v1, v193
	v_readlane_b32 s7, v253, 12
	s_waitcnt vmcnt(6)
	s_mov_b32 s45, 0
	s_cselect_b64 s[18:19], -1, 0
	v_lshl_add_u64 v[202:203], s[6:7], 0, v[0:1]
	v_lshlrev_b32_e32 v0, 14, v12
	v_and_b32_e32 v0, 0xffff8000, v0
	v_lshl_add_u32 v0, v13, 11, v0
	v_and_b32_e32 v1, 1, v12
	v_lshl_or_b32 v0, v1, 6, v0
	v_lshl_add_u32 v204, v14, 1, v0
	v_lshlrev_b32_e32 v0, 14, v9
	v_and_b32_e32 v0, 0xffff8000, v0
	v_lshl_add_u32 v0, v10, 11, v0
	v_and_b32_e32 v1, 1, v9
	v_lshl_or_b32 v0, v1, 6, v0
	v_mov_b32_e32 v205, v193
	v_lshl_add_u32 v206, v11, 1, v0
	v_mov_b32_e32 v207, v193
	v_add_u32_e32 v235, 0, v4
	s_barrier
	s_branch .LBB0_121

.LBB0_564:
	s_andn2_b64 vcc, exec, s[4:5]
	s_cbranch_vccnz .LBB0_647
	v_readlane_b32 s12, v254, 28
	v_mov_b32_e32 v6, v237
	v_readlane_b32 s8, v253, 52
	v_readlane_b32 s13, v254, 29
	v_readlane_b32 s9, v253, 53
	v_readfirstlane_b32 s4, v6
	s_mov_b64 s[10:11], s[14:15]
	s_andn2_b64 vcc, exec, s[12:13]
	s_cbranch_vccnz .LBB0_581
	v_lshlrev_b32_e32 v3, 4, v6
	v_add_u32_e32 v1, 0x2000, v3
	v_ashrrev_i32_e32 v0, 31, v1
	v_lshrrev_b32_e32 v0, 22, v0
	v_add_u32_e32 v0, v1, v0
	v_ashrrev_i32_e32 v0, 10, v0
	v_mul_i32_i24_e32 v2, 0x400, v0
	v_sub_u32_e32 v1, v1, v2
	v_lshrrev_b32_e32 v2, 4, v1
	v_bitop3_b32 v2, v2, v1, 32 bitop3:0x6c
	v_ashrrev_i32_e32 v1, 31, v2
	v_lshrrev_b32_e32 v1, 26, v1
	v_add_u32_e32 v4, v2, v1
	v_lshlrev_b32_e32 v5, 3, v0
	v_ashrrev_i32_e32 v1, 6, v4
	v_and_b32_e32 v5, -16, v5
	v_add_u32_e32 v5, v1, v5
	v_and_b32_e32 v7, 3, v1
	s_mov_b32 s12, 0x1fffe0
	v_lshrrev_b32_e32 v8, 2, v5
	v_lshlrev_b32_e32 v9, 1, v5
	v_and_b32_e32 v4, 0xc0, v4
	v_and_or_b32 v7, v5, s12, v7
	v_and_b32_e32 v8, 4, v8
	v_and_b32_e32 v9, 24, v9
	v_sub_u32_e32 v2, v2, v4
	v_or3_b32 v7, v7, v8, v9
	v_lshlrev_b32_e32 v8, 5, v0
	v_ashrrev_i16_sdwa v2, v252, sext(v2) dst_sel:DWORD dst_unused:UNUSED_PAD src0_sel:DWORD src1_sel:BYTE_0
	v_and_b32_e32 v8, 32, v8
	v_bfe_i32 v2, v2, 0, 16
	v_add_lshl_u32 v4, v8, v2, 1
	s_waitcnt vmcnt(0)
	v_lshl_add_u32 v128, v7, 11, v4
	v_lshl_add_u32 v130, v5, 11, v4
	v_bfe_i32 v4, v6, 27, 1
	v_lshrrev_b32_e32 v4, 22, v4
	v_add_u32_e32 v4, v3, v4
	v_and_b32_e32 v4, 0xfffffc00, v4
	v_sub_u32_e32 v3, v3, v4
	v_lshrrev_b32_e32 v4, 4, v3
	v_bitop3_b32 v5, v4, v3, 32 bitop3:0x6c
	v_ashrrev_i32_e32 v4, 31, v6
	v_lshrrev_b32_e32 v4, 26, v4
	v_ashrrev_i32_e32 v3, 31, v5
	v_add_u32_e32 v4, v6, v4
	v_lshrrev_b32_e32 v3, 26, v3
	v_ashrrev_i32_e32 v4, 6, v4
	v_add_u32_e32 v7, v5, v3
	v_lshlrev_b32_e32 v8, 3, v4
	v_ashrrev_i32_e32 v3, 6, v7
	v_and_b32_e32 v8, -16, v8
	v_add_u32_e32 v8, v3, v8
	v_and_b32_e32 v9, 3, v3
	s_waitcnt lgkmcnt(3)
	v_lshrrev_b32_e32 v10, 2, v8
	s_waitcnt lgkmcnt(2)
	v_lshlrev_b32_e32 v11, 1, v8
	v_and_b32_e32 v7, 0xc0, v7
	s_ashr_i32 s5, s4, 6
	v_and_or_b32 v9, v8, s12, v9
	v_and_b32_e32 v10, 4, v10
	v_and_b32_e32 v11, 24, v11
	v_sub_u32_e32 v5, v5, v7
	s_ashr_i32 s20, s4, 8
	s_lshl_b32 s39, s5, 10
	v_or3_b32 v9, v9, v10, v11
	v_lshlrev_b32_e32 v10, 5, v4
	v_ashrrev_i16_sdwa v5, v252, sext(v5) dst_sel:DWORD dst_unused:UNUSED_PAD src0_sel:DWORD src1_sel:BYTE_0
	v_readlane_b32 s12, v254, 43
	v_and_b32_e32 v10, 32, v10
	v_bfe_i32 v5, v5, 0, 16
	v_readlane_b32 s13, v254, 44
	s_add_u32 s30, s10, s12
	v_add_lshl_u32 v7, v10, v5, 1
	s_addc_u32 s31, s11, s13
	s_add_i32 s40, s39, 0
	v_lshl_add_u32 v192, v9, 11, v7
	s_add_i32 m0, s40, 0x10000
	s_waitcnt vmcnt(6)
	v_lshl_add_u32 v132, v8, 11, v7
	global_load_lds_dwordx4 v192, s[30:31]
	s_add_i32 m0, s40, 0x12000
	s_add_u32 s12, s30, 0x40000
	global_load_lds_dwordx4 v128, s[30:31]
	s_addc_u32 s13, s31, 0
	s_add_i32 m0, s40, 0x14000
	s_nop 0
	global_load_lds_dwordx4 v192, s[12:13]
	s_add_i32 m0, s40, 0x16000
	s_nop 0
	global_load_lds_dwordx4 v128, s[12:13]
	v_readlane_b32 s12, v254, 63
	v_readlane_b32 s13, v255, 0
	s_add_u32 s34, s8, s12
	s_addc_u32 s35, s9, s13
	s_add_i32 s41, s40, 0x2000
	s_mov_b32 m0, s40
	s_add_u32 s12, s34, 0x40000
	global_load_lds_dwordx4 v132, s[34:35]
	s_mov_b32 m0, s41
	s_addc_u32 s13, s35, 0
	s_add_i32 s42, s40, 0x4000
	global_load_lds_dwordx4 v130, s[34:35]
	s_mov_b32 m0, s42
	s_add_i32 s43, s40, 0x6000
	global_load_lds_dwordx4 v132, s[12:13]
	s_mov_b32 m0, s43
	s_nop 0
	global_load_lds_dwordx4 v130, s[12:13]
	v_mov_b32_e32 v129, v193
	v_mov_b32_e32 v133, v193
	v_mov_b32_e32 v131, v193
	v_lshl_add_u64 v[8:9], s[30:31], 0, v[192:193]
	v_lshl_add_u64 v[10:11], s[30:31], 0, v[128:129]
	v_lshl_add_u64 v[12:13], s[34:35], 0, v[132:133]
	v_lshl_add_u64 v[14:15], s[34:35], 0, v[130:131]
	s_add_i32 m0, s40, 0x18000
	v_lshl_add_u64 v[16:17], v[8:9], 0, s[2:3]
	s_add_u32 s12, s30, 0x40080
	s_addc_u32 s13, s31, 0
	global_load_lds_dwordx4 v[16:17], off
	v_lshl_add_u64 v[16:17], v[10:11], 0, s[2:3]
	s_add_i32 m0, s40, 0x1a000
	s_nop 0
	global_load_lds_dwordx4 v[16:17], off
	v_lshl_add_u64 v[16:17], v[12:13], 0, s[2:3]
	s_add_i32 m0, s40, 0x8000
	s_nop 0
	global_load_lds_dwordx4 v[16:17], off
	v_lshl_add_u64 v[16:17], v[14:15], 0, s[2:3]
	s_add_i32 m0, s40, 0xa000
	s_nop 0
	global_load_lds_dwordx4 v[16:17], off
	s_add_i32 m0, s40, 0x1c000
	v_lshl_add_u64 v[16:17], s[12:13], 0, v[192:193]
	global_load_lds_dwordx4 v[16:17], off
	v_lshl_add_u64 v[16:17], s[12:13], 0, v[128:129]
	s_add_i32 m0, s40, 0x1e000
	s_nop 0
	global_load_lds_dwordx4 v[16:17], off
	s_cmp_eq_u32 s20, 1
	s_cselect_b64 s[12:13], -1, 0
	s_cmp_lg_u32 s20, 1
	s_cbranch_scc1 .LBB0_568
	s_barrier
.LBB0_568:
	v_lshrrev_b32_e32 v16, 1, v6
	v_and_b32_e32 v16, 24, v16
	v_and_b32_e32 v7, 15, v6
	v_lshlrev_b32_e32 v17, 1, v16
	v_lshlrev_b32_e32 v6, 2, v6
	s_lshl_b32 s5, s5, 5
	s_waitcnt vmcnt(6)
	v_lshl_or_b32 v140, s20, 6, v7
	v_lshl_or_b32 v7, v7, 6, v17
	s_lshl_b32 s20, s20, 13
	v_and_b32_e32 v6, 32, v6
	s_and_b32 s5, s5, 0x60
	v_lshl_add_u64 v[8:9], s[30:31], 0, v[192:193]
	v_mov_b32_e32 v129, v193
	v_bitop3_b32 v17, v7, s20, v6 bitop3:0xde
	s_lshl_b32 s20, s5, 7
	v_lshl_add_u64 v[10:11], s[30:31], 0, v[128:129]
	v_mov_b32_e32 v133, v193
	v_bitop3_b32 v141, v7, s20, v6 bitop3:0xde
	v_lshl_add_u64 v[12:13], s[34:35], 0, v[132:133]
	v_mov_b32_e32 v131, v193
	s_waitcnt vmcnt(8)
	s_barrier
	s_add_i32 s44, s40, 0x8000
	s_add_i32 s45, s40, 0xa000
	v_lshl_add_u64 v[14:15], s[34:35], 0, v[130:131]
	s_cmpk_lt_u32 s4, 0x100
	v_lshlrev_b32_e32 v6, 14, v0
	v_and_b32_e32 v6, 0xffff8000, v6
	v_lshl_add_u32 v1, v1, 11, v6
	v_and_b32_e32 v0, 1, v0
	v_lshl_or_b32 v0, v0, 6, v1
	v_lshl_add_u32 v134, v2, 1, v0
	v_lshlrev_b32_e32 v0, 14, v4
	v_and_b32_e32 v0, 0xffff8000, v0
	s_waitcnt vmcnt(6)
	v_lshl_add_u32 v0, v3, 11, v0
	v_and_b32_e32 v1, 1, v4
	v_or_b32_e32 v142, s5, v16
	v_lshl_or_b32 v0, v1, 6, v0
	v_readlane_b32 s4, v254, 61
	s_cselect_b64 s[20:21], -1, 0
	v_mov_b32_e32 v135, v193
	v_lshl_add_u32 v136, v5, 1, v0
	v_mov_b32_e32 v137, v193
	s_mov_b32 s46, 0
	v_add_u32_e32 v143, 0, v17
	v_readlane_b32 s47, v254, 42
	s_mov_b32 s48, s4
	s_barrier
	v_readlane_b32 s5, v254, 62
	s_branch .LBB0_571

.LBB0_650:
	s_andn2_b64 vcc, exec, s[4:5]
	s_cbranch_vccnz .LBB0_760
	s_and_b64 s[4:5], s[18:19], exec
	v_readlane_b32 s4, v253, 55
	s_cselect_b32 s21, s4, s97
	v_readlane_b32 s4, v253, 54
	s_cselect_b32 s20, s4, s96
	v_readlane_b32 s4, v254, 34
	v_mov_b32_e32 v12, v237
	v_readlane_b32 s5, v254, 35
	s_cselect_b32 s23, s59, s57
	s_cselect_b32 s22, s60, s33
	s_andn2_b64 vcc, exec, s[4:5]
	v_readfirstlane_b32 s12, v12
	s_cbranch_vccnz .LBB0_762
	v_lshlrev_b32_e32 v0, 4, v12
	v_add_u32_e32 v1, 0x2000, v0
	v_ashrrev_i32_e32 v2, 31, v1
	v_lshrrev_b32_e32 v2, 22, v2
	v_add_u32_e32 v2, v1, v2
	v_ashrrev_i32_e32 v2, 10, v2
	v_mul_i32_i24_e32 v3, 0x400, v2
	v_sub_u32_e32 v1, v1, v3
	v_lshrrev_b32_e32 v3, 4, v1
	v_bitop3_b32 v1, v3, v1, 32 bitop3:0x6c
	v_ashrrev_i32_e32 v3, 31, v1
	v_lshrrev_b32_e32 v3, 26, v3
	v_add_u32_e32 v3, v1, v3
	v_lshlrev_b32_e32 v5, 3, v2
	v_ashrrev_i32_e32 v4, 6, v3
	v_and_b32_e32 v5, -16, v5
	v_lshlrev_b32_e32 v2, 5, v2
	s_and_b64 s[4:5], s[18:19], exec
	v_add_u32_e32 v5, v4, v5
	v_and_b32_e32 v13, 32, v2
	v_and_b32_e32 v2, 0xc0, v3
	v_and_b32_e32 v4, 3, v4
	s_mov_b32 s5, 0xffffe0
	v_lshrrev_b32_e32 v6, 2, v5
	v_lshlrev_b32_e32 v7, 1, v5
	v_sub_u32_e32 v1, v1, v2
	s_movk_i32 s4, 0x400
	v_and_or_b32 v4, v5, s5, v4
	v_and_b32_e32 v6, 4, v6
	v_and_b32_e32 v7, 24, v7
	v_ashrrev_i16_sdwa v1, v252, sext(v1) dst_sel:DWORD dst_unused:UNUSED_PAD src0_sel:DWORD src1_sel:BYTE_0
	s_cselect_b32 s4, s4, 0xb00
	v_or3_b32 v4, v4, v6, v7
	v_bfe_i32 v14, v1, 0, 16
	v_mul_u32_u24_e32 v4, s4, v4
	v_add_u32_e32 v1, v13, v14
	v_mul_lo_u32 v15, v5, s4
	v_add_lshl_u32 v176, v4, v1, 1
	v_add_lshl_u32 v178, v1, v15, 1
	v_bfe_i32 v1, v12, 27, 1
	v_lshrrev_b32_e32 v1, 22, v1
	v_add_u32_e32 v1, v0, v1
	v_and_b32_e32 v1, 0xfffffc00, v1
	v_sub_u32_e32 v0, v0, v1
	v_lshrrev_b32_e32 v1, 4, v0
	v_ashrrev_i32_e32 v3, 31, v12
	v_bitop3_b32 v0, v1, v0, 32 bitop3:0x6c
	v_lshrrev_b32_e32 v3, 26, v3
	v_ashrrev_i32_e32 v1, 31, v0
	v_add_u32_e32 v3, v12, v3
	v_lshrrev_b32_e32 v1, 26, v1
	v_ashrrev_i32_e32 v3, 6, v3
	v_add_u32_e32 v1, v0, v1
	v_lshlrev_b32_e32 v4, 3, v3
	v_ashrrev_i32_e32 v2, 6, v1
	v_and_b32_e32 v4, -16, v4
	s_lshl_b32 s61, s4, 9
	v_add_u32_e32 v4, v2, v4
	v_and_b32_e32 v2, 3, v2
	v_readlane_b32 s10, v254, 39
	v_and_or_b32 v2, v4, s5, v2
	v_and_b32_e32 v1, 0xc0, v1
	s_mul_hi_i32 s5, s61, s10
	s_mul_i32 s13, s61, s10
	v_readlane_b32 s10, v254, 47
	s_ashr_i32 s8, s12, 6
	v_lshrrev_b32_e32 v5, 2, v4
	v_lshlrev_b32_e32 v6, 1, v4
	v_sub_u32_e32 v0, v0, v1
	v_readlane_b32 s11, v254, 48
	s_mov_b32 s24, s10
	s_ashr_i32 s9, s12, 8
	s_lshl_b32 s80, s4, 8
	s_lshl_b32 s62, s8, 10
	v_and_b32_e32 v5, 4, v5
	v_and_b32_e32 v6, 24, v6
	v_lshlrev_b32_e32 v3, 5, v3
	v_ashrrev_i16_sdwa v0, v252, sext(v0) dst_sel:DWORD dst_unused:UNUSED_PAD src0_sel:DWORD src1_sel:BYTE_0
	s_mul_i32 s11, s61, s24
	v_or3_b32 v2, v2, v5, v6
	v_and_b32_e32 v16, 32, v3
	v_bfe_i32 v17, v0, 0, 16
	s_mul_hi_i32 s10, s61, s10
	s_add_u32 s52, s22, s11
	v_mul_u32_u24_e32 v2, s4, v2
	v_add_u32_e32 v0, v16, v17
	s_addc_u32 s53, s23, s10
	s_add_i32 s63, s62, 0
	v_add_lshl_u32 v192, v2, v0, 1
	s_add_i32 m0, s63, 0x10000
	v_mul_lo_u32 v18, v4, s4
	global_load_lds_dwordx4 v192, s[52:53]
	s_add_i32 m0, s63, 0x12000
	s_add_u32 s10, s52, s80
	global_load_lds_dwordx4 v176, s[52:53]
	s_addc_u32 s11, s53, 0
	s_add_i32 m0, s63, 0x14000
	v_mov_b32_e32 v177, v193
	global_load_lds_dwordx4 v192, s[10:11]
	s_add_i32 m0, s63, 0x16000
	s_add_u32 s54, s20, s13
	s_addc_u32 s55, s21, s5
	s_add_i32 s64, s63, 0x2000
	v_add_lshl_u32 v180, v0, v18, 1
	v_lshl_add_u64 v[4:5], s[10:11], 0, v[192:193]
	v_lshl_add_u64 v[6:7], s[10:11], 0, v[176:177]
	global_load_lds_dwordx4 v176, s[10:11]
	s_mov_b32 m0, s63
	s_add_u32 s10, s54, s80
	global_load_lds_dwordx4 v180, s[54:55]
	s_mov_b32 m0, s64
	s_addc_u32 s11, s55, 0
	s_add_i32 s65, s63, 0x4000
	global_load_lds_dwordx4 v178, s[54:55]
	s_mov_b32 m0, s65
	s_add_i32 s66, s63, 0x6000
	global_load_lds_dwordx4 v180, s[10:11]
	s_mov_b32 m0, s66
	v_mov_b32_e32 v181, v193
	global_load_lds_dwordx4 v178, s[10:11]
	v_mov_b32_e32 v179, v193
	v_lshl_add_u64 v[0:1], s[52:53], 0, v[192:193]
	v_lshl_add_u64 v[2:3], s[52:53], 0, v[176:177]
	v_lshl_add_u64 v[8:9], s[54:55], 0, v[180:181]
	v_lshl_add_u64 v[10:11], s[54:55], 0, v[178:179]
	s_add_i32 m0, s63, 0x18000
	v_lshl_add_u64 v[0:1], v[0:1], 0, s[2:3]
	s_nop 0
	global_load_lds_dwordx4 v[0:1], off
	v_lshl_add_u64 v[0:1], v[2:3], 0, s[2:3]
	s_add_i32 m0, s63, 0x1a000
	s_nop 0
	global_load_lds_dwordx4 v[0:1], off
	v_lshl_add_u64 v[0:1], v[8:9], 0, s[2:3]
	s_add_i32 m0, s63, 0x8000
	s_nop 0
	global_load_lds_dwordx4 v[0:1], off
	v_lshl_add_u64 v[0:1], v[10:11], 0, s[2:3]
	s_add_i32 m0, s63, 0xa000
	s_nop 0
	global_load_lds_dwordx4 v[0:1], off
	s_add_i32 m0, s63, 0x1c000
	v_lshl_add_u64 v[0:1], v[4:5], 0, s[2:3]
	global_load_lds_dwordx4 v[0:1], off
	v_lshl_add_u64 v[0:1], v[6:7], 0, s[2:3]
	s_add_i32 m0, s63, 0x1e000
	s_nop 0
	global_load_lds_dwordx4 v[0:1], off
	s_cmp_eq_u32 s9, 1
	v_readlane_b32 s68, v253, 13
	s_waitcnt lgkmcnt(0)
	s_cselect_b64 s[24:25], -1, 0
	s_cmp_lg_u32 s9, 1
	v_readlane_b32 s69, v253, 14
	s_cbranch_scc1 .LBB0_654
	s_barrier
.LBB0_654:
	v_readlane_b32 s5, v255, 23
	s_or_b32 s5, s67, s5
	s_cmp_eq_u32 s5, 0
	v_readlane_b32 s5, v255, 6
	v_readlane_b32 s36, v253, 15
	s_cselect_b64 s[10:11], -1, 0
	s_or_b32 s5, s67, s5
	v_readlane_b32 s37, v253, 16
	v_readlane_b32 s42, v253, 21
	v_readlane_b32 s43, v253, 22
	v_readlane_b32 s28, v255, 4
	s_cmp_eq_u32 s5, 0
	v_readlane_b32 s38, v253, 17
	v_readlane_b32 s39, v253, 18
	v_readlane_b32 s40, v253, 19
	v_readlane_b32 s41, v253, 20
	v_readlane_b32 s44, v253, 23
	v_readlane_b32 s45, v253, 24
	v_readlane_b32 s46, v253, 25
	v_readlane_b32 s47, v253, 26
	v_readlane_b32 s48, v253, 27
	v_readlane_b32 s49, v253, 28
	v_readlane_b32 s50, v253, 29
	v_readlane_b32 s51, v253, 30
	s_mov_b64 s[78:79], s[42:43]
	s_mov_b64 s[72:73], s[36:37]
	v_readlane_b32 s29, v255, 5
	s_mov_b64 s[76:77], s[40:41]
	s_cselect_b32 s27, s73, 0
	s_cselect_b32 s26, s72, 0
	s_and_b64 s[6:7], s[28:29], s[6:7]
	v_readlane_b32 s36, v253, 31
	s_and_b64 s[6:7], s[6:7], exec
	v_readlane_b32 s50, v253, 45
	v_readlane_b32 s51, v253, 46
	s_cselect_b32 s29, s51, 0
	s_cselect_b32 s28, s50, 0
	s_or_b32 s6, s67, s58
	s_mov_b32 s7, s81
	s_lshl_b64 s[34:35], s[6:7], 12
	s_add_u32 s30, s76, s34
	s_addc_u32 s31, s77, s35
	s_add_u32 s34, s78, s34
	s_addc_u32 s35, s79, s35
	s_lshl_b64 s[6:7], s[6:7], 15
	s_add_u32 s67, s68, s6
	s_addc_u32 s68, s69, s7
	s_waitcnt vmcnt(8)
	s_barrier
	s_add_i32 s69, s63, 0x8000
	s_add_i32 s70, s63, 0xa000
	v_and_b32_e32 v3, 48, v12
	v_lshlrev_b32_e32 v4, 2, v12
	v_and_b32_e32 v1, 15, v12
	s_and_b32 s6, s8, 3
	s_lshr_b32 s72, s4, 6
	s_lshl_b32 s4, s9, 13
	v_lshl_or_b32 v3, v1, 6, v3
	v_and_b32_e32 v4, 32, v4
	v_lshrrev_b32_e32 v2, 1, v12
	v_bitop3_b32 v5, v3, s4, v4 bitop3:0xde
	s_lshl_b32 s4, s6, 12
	s_add_i32 s73, s72, -2
	v_readlane_b32 s37, v253, 32
	v_and_b32_e32 v2, 24, v2
	s_cmpk_lt_u32 s12, 0x100
	v_and_b32_e32 v0, 63, v12
	v_lshl_or_b32 v204, s6, 5, v2
	s_cselect_b64 s[36:37], -1, 0
	s_lshl_b32 s6, s6, 3
	v_lshlrev_b32_e32 v2, 2, v0
	s_add_i32 s6, s6, 0
	s_lshl_b32 s7, s9, 11
	v_readlane_b32 s40, v253, 35
	v_readlane_b32 s41, v253, 36
	v_lshl_or_b32 v202, s9, 6, v1
	v_xor_b32_e32 v205, 64, v2
	v_xor_b32_e32 v206, 0x80, v2
	s_add_i32 s6, s6, s7
	v_lshlrev_b32_e32 v2, 5, v1
	v_and_b32_e32 v1, 31, v12
	v_bitop3_b32 v203, v3, s4, v4 bitop3:0xde
	v_cmp_gt_u32_e64 s[4:5], 16, v0
	s_add_i32 s13, s6, 0x20000
	v_lshl_or_b32 v207, s8, 5, v1
	v_cmp_gt_u32_e64 s[6:7], 32, v0
	v_cmp_eq_u32_e64 s[8:9], 0, v0
	v_readlane_b32 s40, v254, 49
	v_add_u32_e32 v0, v15, v13
	v_readlane_b32 s38, v253, 33
	v_readlane_b32 s39, v253, 34
	s_cmp_lt_u32 s12, 64
	v_readlane_b32 s41, v254, 50
	v_add_lshl_u32 v0, v0, v14, 1
	v_mov_b32_e32 v1, v193
	s_cselect_b64 s[38:39], -1, 0
	s_and_b64 s[40:41], s[10:11], s[40:41]
	v_lshl_add_u64 v[182:183], s[80:81], 0, v[0:1]
	v_add_u32_e32 v0, v18, v16
	v_readlane_b32 s42, v253, 37
	v_readlane_b32 s43, v253, 38
	s_waitcnt vmcnt(6)
	v_lshlrev_b32_e32 v3, 5, v207
	s_cmp_lg_u64 s[26:27], 0
	v_add_lshl_u32 v0, v0, v17, 1
	v_readlane_b32 s44, v253, 39
	v_readlane_b32 s45, v253, 40
	v_readlane_b32 s12, v254, 56
	v_or_b32_e32 v210, 16, v202
	v_or_b32_e32 v212, 32, v202
	v_or_b32_e32 v214, 48, v202
	v_add_u32_e32 v216, 0x80, v202
	v_add_u32_e32 v218, 0x90, v202
	v_add_u32_e32 v220, 0xa0, v202
	v_add_u32_e32 v222, 0xb0, v202
	s_cselect_b64 s[42:43], -1, 0
	s_cmp_lg_u64 s[28:29], 0
	v_lshl_add_u64 v[184:185], s[80:81], 0, v[0:1]
	v_add_u32_e32 v0, 0, v3
	v_readlane_b32 s10, v254, 46
	s_mov_b32 s71, 0
	v_lshl_add_u32 v208, v207, 3, s12
	v_lshl_add_u32 v209, v202, 3, s12
	v_lshl_add_u32 v211, v210, 3, s12
	v_lshl_add_u32 v213, v212, 3, s12
	v_lshl_add_u32 v215, v214, 3, s12
	v_lshl_add_u32 v217, v216, 3, s12
	v_lshl_add_u32 v219, v218, 3, s12
	v_lshl_add_u32 v221, v220, 3, s12
	v_lshl_add_u32 v223, v222, 3, s12
	v_add_u32_e32 v231, 0, v5
	v_add_u32_e32 v232, 0x20000, v0
	v_add_u32_e32 v233, s13, v2
	v_readlane_b32 s78, v254, 39
	s_cselect_b64 s[44:45], -1, 0
	s_mov_b32 s50, s10
	v_readlane_b32 s46, v253, 41
	v_readlane_b32 s47, v253, 42
	v_readlane_b32 s48, v253, 43
	v_readlane_b32 s49, v253, 44
	s_barrier
	s_branch .LBB0_657
